# L0 out-projection epilogue: paired 8-byte bf16 stores merged into 16-byte stores via v_permlane16_swap (waitcnts re-derived)
# baseline (speedup 1.0000x reference)
.LBB0_748:
	s_lshl_b64 s[88:89], s[74:75], 19
	s_add_u32 s88, s67, s88
	s_addc_u32 s89, s80, s89
	s_lshr_b32 s8, s8, 2
	s_add_i32 s8, s8, 1
	s_and_b64 s[90:91], s[90:91], exec
	s_cselect_b32 s8, 0, s8
	s_lshl_b64 s[76:77], s[76:77], 19
	s_add_u32 s31, s68, s76
	s_addc_u32 s35, s69, s77
	s_lshl_b32 s76, s78, 2
	s_add_u32 s90, s31, s76
	v_lshl_or_b32 v174, s92, 8, v179
	s_addc_u32 s91, s35, 0
	v_ashrrev_i32_e32 v175, 31, v174
	s_mul_hi_u32 s31, s8, 0x6000
	s_mulk_i32 s8, 0x6000
	s_lshl_b64 s[74:75], s[74:75], 10
	s_add_u32 s76, s63, s8
	v_lshl_add_u64 v[172:173], v[132:133], 0, v[174:175]
	s_addc_u32 s77, s64, s31
	v_lshlrev_b64 v[214:215], 2, v[174:175]
	v_lshl_add_u64 v[198:199], v[172:173], 2, s[86:87]
	v_lshl_add_u64 v[176:177], s[76:77], 0, v[214:215]
	global_load_dwordx4 v[182:185], v[198:199], off
	global_load_dwordx4 v[186:189], v[176:177], off
	v_lshlrev_b64 v[216:217], 1, v[172:173]
	s_add_u32 s76, s65, s8
	v_lshl_add_u64 v[218:219], s[90:91], 0, v[216:217]
	s_addc_u32 s77, s66, s31
	global_load_dwordx4 v[190:193], v[198:199], off offset:64
	global_load_dwordx4 v[194:197], v[198:199], off offset:512
	s_nop 0
	global_load_dwordx4 v[198:201], v[198:199], off offset:576
	s_nop 0
	global_load_dwordx4 v[202:205], v[176:177], off offset:64
	global_load_dwordx4 v[206:209], v[176:177], off offset:512
	global_load_dwordx4 v[210:213], v[176:177], off offset:576
	v_lshl_add_u64 v[172:173], s[76:77], 0, v[214:215]
	v_and_b32_e32 v248, 16, v230
	v_lshrrev_b32_e32 v249, 1, v248
	v_add_u32_e32 v248, v248, v249
	v_mov_b32_e32 v249, 0
	s_waitcnt vmcnt(0)
	v_pk_fma_f32 v[126:127], v[126:127], v[188:189], v[184:185]
	v_pk_fma_f32 v[220:221], v[124:125], v[186:187], v[182:183]
	v_cvt_pk_bf16_f32 v125, v126, v127
	v_cvt_pk_bf16_f32 v124, v220, v221
	v_mov_b32_e32 v224, v124
	v_mov_b32_e32 v225, v125
	global_load_dwordx4 v[182:185], v[172:173], off
	v_lshl_add_u64 v[124:125], s[50:51], 0, v[214:215]
	global_load_dwordx4 v[186:189], v[124:125], off
	v_pk_fma_f32 v[192:193], v[122:123], v[204:205], v[192:193]
	v_lshl_add_u64 v[214:215], s[88:89], 0, v[216:217]
	v_pk_fma_f32 v[190:191], v[120:121], v[202:203], v[190:191]
	v_cvt_pk_bf16_f32 v121, v192, v193
	v_cvt_pk_bf16_f32 v120, v190, v191
	s_waitcnt vmcnt(1)
	v_pk_add_f32 v[122:123], v[184:185], 1.0 op_sel_hi:[1,0]
	v_pk_add_f32 v[182:183], v[182:183], 1.0 op_sel_hi:[1,0]
	s_waitcnt vmcnt(0)
	v_pk_mul_f32 v[122:123], v[188:189], v[122:123]
	v_pk_mul_f32 v[182:183], v[186:187], v[182:183]
	v_pk_mul_f32 v[122:123], v[126:127], v[122:123]
	v_pk_mul_f32 v[182:183], v[220:221], v[182:183]
	v_pk_fma_f32 v[186:187], v[118:119], v[208:209], v[196:197]
	v_cvt_pk_bf16_f32 v182, v182, v183
	v_cvt_pk_bf16_f32 v183, v122, v123
	v_mov_b32_e32 v232, v182
	v_mov_b32_e32 v233, v183
	v_mov_b32_e32 v226, v120
	v_mov_b32_e32 v227, v121
	s_nop 1
	v_permlane16_swap_b32_e32 v224, v226
	v_permlane16_swap_b32_e32 v225, v227
	v_lshl_add_u64 v[244:245], v[218:219], 0, v[248:249]
	global_store_dwordx4 v[244:245], v[224:227], off
	global_load_dwordx4 v[120:123], v[172:173], off offset:64
	s_nop 0
	global_load_dwordx4 v[182:185], v[124:125], off offset:64
	v_pk_fma_f32 v[188:189], v[116:117], v[206:207], v[194:195]
	v_cvt_pk_bf16_f32 v117, v186, v187
	v_cvt_pk_bf16_f32 v116, v188, v189
	s_waitcnt vmcnt(1)
	v_pk_add_f32 v[118:119], v[122:123], 1.0 op_sel_hi:[1,0]
	v_pk_add_f32 v[120:121], v[120:121], 1.0 op_sel_hi:[1,0]
	s_waitcnt vmcnt(0)
	v_pk_mul_f32 v[118:119], v[184:185], v[118:119]
	v_pk_mul_f32 v[120:121], v[182:183], v[120:121]
	v_pk_mul_f32 v[118:119], v[192:193], v[118:119]
	v_pk_mul_f32 v[120:121], v[190:191], v[120:121]
	v_pk_fma_f32 v[182:183], v[114:115], v[212:213], v[200:201]
	v_cvt_pk_bf16_f32 v120, v120, v121
	v_cvt_pk_bf16_f32 v121, v118, v119
	v_mov_b32_e32 v234, v120
	v_mov_b32_e32 v235, v121
	s_nop 1
	v_permlane16_swap_b32_e32 v232, v234
	v_permlane16_swap_b32_e32 v233, v235
	v_lshl_add_u64 v[246:247], v[214:215], 0, v[248:249]
	global_store_dwordx4 v[246:247], v[232:235], off
	v_mov_b32_e32 v236, v116
	v_mov_b32_e32 v237, v117
	global_load_dwordx4 v[116:119], v[172:173], off offset:512
	s_nop 0
	global_load_dwordx4 v[120:123], v[124:125], off offset:512
	v_pk_fma_f32 v[184:185], v[112:113], v[210:211], v[198:199]
	v_cvt_pk_bf16_f32 v113, v182, v183
	v_cvt_pk_bf16_f32 v112, v184, v185
	v_mul_f32_e32 v194, v183, v183
	v_fmac_f32_e32 v194, v182, v182
	s_waitcnt vmcnt(1)
	v_pk_add_f32 v[114:115], v[118:119], 1.0 op_sel_hi:[1,0]
	v_pk_add_f32 v[116:117], v[116:117], 1.0 op_sel_hi:[1,0]
	s_waitcnt vmcnt(0)
	v_pk_mul_f32 v[114:115], v[122:123], v[114:115]
	v_pk_mul_f32 v[116:117], v[120:121], v[116:117]
	v_pk_mul_f32 v[114:115], v[186:187], v[114:115]
	v_pk_mul_f32 v[116:117], v[188:189], v[116:117]
	v_mul_f32_e32 v189, v189, v189
	v_cvt_pk_bf16_f32 v116, v116, v117
	v_cvt_pk_bf16_f32 v117, v114, v115
	v_mov_b32_e32 v240, v116
	v_mov_b32_e32 v241, v117
	v_mov_b32_e32 v238, v112
	v_mov_b32_e32 v239, v113
	s_nop 1
	v_permlane16_swap_b32_e32 v236, v238
	v_permlane16_swap_b32_e32 v237, v239
	v_lshl_add_u64 v[244:245], v[218:219], 0, v[248:249]
	global_store_dwordx4 v[244:245], v[236:239], off offset:256
	global_load_dwordx4 v[116:119], v[172:173], off offset:576
	s_nop 0
	global_load_dwordx4 v[120:123], v[124:125], off offset:576
	v_mul_f32_e32 v114, v221, v221
	v_mul_f32_e32 v115, v127, v127
	v_mul_f32_e32 v127, v191, v191
	v_mul_f32_e32 v191, v193, v193
	v_and_b32_e32 v113, 64, v181
	v_mul_f32_e32 v187, v187, v187
	v_fmac_f32_e32 v114, v220, v220
	v_fmac_f32_e32 v115, v126, v126
	v_fmac_f32_e32 v127, v190, v190
	v_fmac_f32_e32 v191, v192, v192
	v_xor_b32_e32 v112, 16, v181
	v_add_u32_e32 v113, 64, v113
	v_mul_f32_e32 v193, v185, v185
	v_fmac_f32_e32 v189, v188, v188
	v_fmac_f32_e32 v187, v186, v186
	v_add_f32_e32 v114, v114, v115
	v_add_f32_e32 v115, v127, v191
	v_cmp_lt_i32_e32 vcc, v112, v113
	v_fmac_f32_e32 v193, v184, v184
	v_add_f32_e32 v126, v189, v187
	v_add_f32_e32 v114, v114, v115
	v_cndmask_b32_e32 v112, v181, v112, vcc
	v_add_f32_e32 v127, v193, v194
	v_add_f32_e32 v114, v114, v126
	v_lshlrev_b32_e32 v112, 2, v112
	v_add_f32_e32 v114, v114, v127
	ds_bpermute_b32 v115, v112, v114
	v_xor_b32_e32 v126, 32, v181
	v_cmp_lt_i32_e32 vcc, v126, v113
	s_waitcnt lgkmcnt(0)
	v_add_f32_e32 v114, v114, v115
	v_cndmask_b32_e32 v113, v181, v126, vcc
	v_lshlrev_b32_e32 v113, 2, v113
	ds_bpermute_b32 v115, v113, v114
	s_waitcnt vmcnt(1)
	v_pk_add_f32 v[118:119], v[118:119], 1.0 op_sel_hi:[1,0]
	v_pk_add_f32 v[116:117], v[116:117], 1.0 op_sel_hi:[1,0]
	s_waitcnt vmcnt(0)
	v_pk_mul_f32 v[118:119], v[122:123], v[118:119]
	v_pk_mul_f32 v[116:117], v[120:121], v[116:117]
	v_pk_mul_f32 v[118:119], v[182:183], v[118:119]
	v_pk_mul_f32 v[116:117], v[184:185], v[116:117]
	s_nop 0
	v_cvt_pk_bf16_f32 v116, v116, v117
	v_cvt_pk_bf16_f32 v117, v118, v119
	v_mov_b32_e32 v242, v116
	v_mov_b32_e32 v243, v117
	s_nop 1
	v_permlane16_swap_b32_e32 v240, v242
	v_permlane16_swap_b32_e32 v241, v243
	v_lshl_add_u64 v[246:247], v[214:215], 0, v[248:249]
	global_store_dwordx4 v[246:247], v[240:243], off offset:256
	s_and_saveexec_b64 s[76:77], s[0:1]
	s_cbranch_execz .LBB0_750
	s_waitcnt lgkmcnt(0)
	v_add_f32_e32 v116, v114, v115
	v_lshl_add_u64 v[114:115], v[148:149], 0, s[74:75]
	global_atomic_add_f32 v[114:115], v116, off
.LBB0_750:
	s_or_b64 exec, exec, s[76:77]
	v_lshl_add_u64 v[122:123], v[134:135], 0, v[174:175]
	v_lshl_add_u64 v[126:127], v[122:123], 2, s[86:87]
	s_waitcnt lgkmcnt(0)
	global_load_dwordx4 v[114:117], v[126:127], off
	global_load_dwordx4 v[118:121], v[176:177], off
	global_load_dwordx4 v[182:185], v[176:177], off offset:64
	global_load_dwordx4 v[186:189], v[176:177], off offset:512
	global_load_dwordx4 v[190:193], v[176:177], off offset:576
	v_lshlrev_b64 v[122:123], 1, v[122:123]
	global_load_dwordx4 v[194:197], v[126:127], off offset:64
	global_load_dwordx4 v[198:201], v[126:127], off offset:512
	global_load_dwordx4 v[202:205], v[126:127], off offset:576
	v_lshl_add_u64 v[126:127], s[90:91], 0, v[122:123]
	v_lshl_add_u64 v[122:123], s[88:89], 0, v[122:123]
	s_waitcnt vmcnt(6)
	v_pk_fma_f32 v[120:121], v[110:111], v[120:121], v[116:117]
	v_pk_fma_f32 v[118:119], v[108:109], v[118:119], v[114:115]
	v_cvt_pk_bf16_f32 v109, v120, v121
	v_cvt_pk_bf16_f32 v108, v118, v119
	v_mov_b32_e32 v224, v108
	v_mov_b32_e32 v225, v109
	global_load_dwordx4 v[108:111], v[172:173], off
	s_nop 0
	global_load_dwordx4 v[114:117], v[124:125], off
	s_waitcnt vmcnt(4)
	v_pk_fma_f32 v[184:185], v[106:107], v[184:185], v[196:197]
	v_pk_fma_f32 v[182:183], v[104:105], v[182:183], v[194:195]
	v_cvt_pk_bf16_f32 v105, v184, v185
	v_cvt_pk_bf16_f32 v104, v182, v183
	s_waitcnt vmcnt(1)
	v_pk_add_f32 v[106:107], v[110:111], 1.0 op_sel_hi:[1,0]
	v_pk_add_f32 v[108:109], v[108:109], 1.0 op_sel_hi:[1,0]
	s_waitcnt vmcnt(0)
	v_pk_mul_f32 v[106:107], v[116:117], v[106:107]
	v_pk_mul_f32 v[108:109], v[114:115], v[108:109]
	v_pk_mul_f32 v[106:107], v[120:121], v[106:107]
	v_pk_mul_f32 v[108:109], v[118:119], v[108:109]
	v_pk_fma_f32 v[114:115], v[102:103], v[188:189], v[200:201]
	v_cvt_pk_bf16_f32 v108, v108, v109
	v_cvt_pk_bf16_f32 v109, v106, v107
	v_mov_b32_e32 v232, v108
	v_mov_b32_e32 v233, v109
	v_mov_b32_e32 v226, v104
	v_mov_b32_e32 v227, v105
	s_nop 1
	v_permlane16_swap_b32_e32 v224, v226
	v_permlane16_swap_b32_e32 v225, v227
	v_lshl_add_u64 v[244:245], v[126:127], 0, v[248:249]
	global_store_dwordx4 v[244:245], v[224:227], off
	global_load_dwordx4 v[104:107], v[172:173], off offset:64
	s_nop 0
	global_load_dwordx4 v[108:111], v[124:125], off offset:64
	v_pk_fma_f32 v[116:117], v[100:101], v[186:187], v[198:199]
	v_cvt_pk_bf16_f32 v101, v114, v115
	v_cvt_pk_bf16_f32 v100, v116, v117
	s_waitcnt vmcnt(1)
	v_pk_add_f32 v[102:103], v[106:107], 1.0 op_sel_hi:[1,0]
	v_pk_add_f32 v[104:105], v[104:105], 1.0 op_sel_hi:[1,0]
	s_waitcnt vmcnt(0)
	v_pk_mul_f32 v[102:103], v[110:111], v[102:103]
	v_pk_mul_f32 v[104:105], v[108:109], v[104:105]
	v_pk_mul_f32 v[102:103], v[184:185], v[102:103]
	v_pk_mul_f32 v[104:105], v[182:183], v[104:105]
	v_pk_fma_f32 v[108:109], v[98:99], v[192:193], v[204:205]
	v_cvt_pk_bf16_f32 v104, v104, v105
	v_cvt_pk_bf16_f32 v105, v102, v103
	v_mov_b32_e32 v234, v104
	v_mov_b32_e32 v235, v105
	s_nop 1
	v_permlane16_swap_b32_e32 v232, v234
	v_permlane16_swap_b32_e32 v233, v235
	v_lshl_add_u64 v[246:247], v[122:123], 0, v[248:249]
	global_store_dwordx4 v[246:247], v[232:235], off
	v_mov_b32_e32 v236, v100
	v_mov_b32_e32 v237, v101
	global_load_dwordx4 v[100:103], v[172:173], off offset:512
	s_nop 0
	global_load_dwordx4 v[104:107], v[124:125], off offset:512
	v_pk_fma_f32 v[110:111], v[96:97], v[190:191], v[202:203]
	v_cvt_pk_bf16_f32 v97, v108, v109
	v_cvt_pk_bf16_f32 v96, v110, v111
	s_waitcnt vmcnt(1)
	v_pk_add_f32 v[98:99], v[102:103], 1.0 op_sel_hi:[1,0]
	v_pk_add_f32 v[100:101], v[100:101], 1.0 op_sel_hi:[1,0]
	s_waitcnt vmcnt(0)
	v_pk_mul_f32 v[98:99], v[106:107], v[98:99]
	v_pk_mul_f32 v[100:101], v[104:105], v[100:101]
	v_pk_mul_f32 v[98:99], v[114:115], v[98:99]
	v_pk_mul_f32 v[100:101], v[116:117], v[100:101]
	v_mul_f32_e32 v106, v183, v183
	v_cvt_pk_bf16_f32 v100, v100, v101
	v_cvt_pk_bf16_f32 v101, v98, v99
	v_mov_b32_e32 v240, v100
	v_mov_b32_e32 v241, v101
	v_mov_b32_e32 v238, v96
	v_mov_b32_e32 v239, v97
	s_nop 1
	v_permlane16_swap_b32_e32 v236, v238
	v_permlane16_swap_b32_e32 v237, v239
	v_lshl_add_u64 v[244:245], v[126:127], 0, v[248:249]
	global_store_dwordx4 v[244:245], v[236:239], off offset:256
	global_load_dwordx4 v[98:101], v[172:173], off offset:576
	s_nop 0
	global_load_dwordx4 v[102:105], v[124:125], off offset:576
	v_mul_f32_e32 v96, v119, v119
	v_mul_f32_e32 v97, v121, v121
	v_mul_f32_e32 v107, v185, v185
	v_mul_f32_e32 v117, v117, v117
	v_mul_f32_e32 v115, v115, v115
	v_fmac_f32_e32 v96, v118, v118
	v_fmac_f32_e32 v97, v120, v120
	v_fmac_f32_e32 v106, v182, v182
	v_fmac_f32_e32 v107, v184, v184
	v_mul_f32_e32 v119, v111, v111
	v_mul_f32_e32 v121, v109, v109
	v_fmac_f32_e32 v117, v116, v116
	v_fmac_f32_e32 v115, v114, v114
	v_add_f32_e32 v96, v96, v97
	v_add_f32_e32 v97, v106, v107
	v_fmac_f32_e32 v119, v110, v110
	v_fmac_f32_e32 v121, v108, v108
	v_add_f32_e32 v106, v117, v115
	v_add_f32_e32 v96, v96, v97
	v_add_f32_e32 v107, v119, v121
	v_add_f32_e32 v96, v96, v106
	v_add_f32_e32 v96, v96, v107
	ds_bpermute_b32 v97, v112, v96
	s_waitcnt lgkmcnt(0)
	v_add_f32_e32 v96, v96, v97
	ds_bpermute_b32 v97, v113, v96
	s_waitcnt vmcnt(1)
	v_pk_add_f32 v[100:101], v[100:101], 1.0 op_sel_hi:[1,0]
	v_pk_add_f32 v[98:99], v[98:99], 1.0 op_sel_hi:[1,0]
	s_waitcnt vmcnt(0)
	v_pk_mul_f32 v[100:101], v[104:105], v[100:101]
	v_pk_mul_f32 v[98:99], v[102:103], v[98:99]
	v_pk_mul_f32 v[100:101], v[108:109], v[100:101]
	v_pk_mul_f32 v[98:99], v[110:111], v[98:99]
	s_nop 0
	v_cvt_pk_bf16_f32 v98, v98, v99
	v_cvt_pk_bf16_f32 v99, v100, v101
	v_mov_b32_e32 v242, v98
	v_mov_b32_e32 v243, v99
	s_nop 1
	v_permlane16_swap_b32_e32 v240, v242
	v_permlane16_swap_b32_e32 v241, v243
	v_lshl_add_u64 v[246:247], v[122:123], 0, v[248:249]
	global_store_dwordx4 v[246:247], v[240:243], off offset:256
	s_and_saveexec_b64 s[76:77], s[0:1]
	s_cbranch_execz .LBB0_752
	s_waitcnt lgkmcnt(0)
	v_add_f32_e32 v98, v96, v97
	v_lshl_add_u64 v[96:97], v[150:151], 0, s[74:75]
	global_atomic_add_f32 v[96:97], v98, off
.LBB0_752:
	s_or_b64 exec, exec, s[76:77]
	v_lshl_add_u64 v[118:119], v[136:137], 0, v[174:175]
	v_lshl_add_u64 v[122:123], v[118:119], 2, s[86:87]
	s_waitcnt lgkmcnt(0)
	global_load_dwordx4 v[96:99], v[122:123], off
	global_load_dwordx4 v[100:103], v[176:177], off
	global_load_dwordx4 v[104:107], v[176:177], off offset:64
	global_load_dwordx4 v[108:111], v[176:177], off offset:512
	global_load_dwordx4 v[114:117], v[176:177], off offset:576
	v_lshlrev_b64 v[126:127], 1, v[118:119]
	global_load_dwordx4 v[118:121], v[122:123], off offset:64
	global_load_dwordx4 v[182:185], v[122:123], off offset:512
	global_load_dwordx4 v[186:189], v[122:123], off offset:576
	v_lshl_add_u64 v[122:123], s[90:91], 0, v[126:127]
	v_lshl_add_u64 v[126:127], s[88:89], 0, v[126:127]
	s_waitcnt vmcnt(6)
	v_pk_fma_f32 v[102:103], v[94:95], v[102:103], v[98:99]
	v_pk_fma_f32 v[100:101], v[92:93], v[100:101], v[96:97]
	v_cvt_pk_bf16_f32 v93, v102, v103
	v_cvt_pk_bf16_f32 v92, v100, v101
	v_mov_b32_e32 v224, v92
	v_mov_b32_e32 v225, v93
	global_load_dwordx4 v[92:95], v[172:173], off
	s_nop 0
	global_load_dwordx4 v[96:99], v[124:125], off
	s_waitcnt vmcnt(4)
	v_pk_fma_f32 v[106:107], v[90:91], v[106:107], v[120:121]
	v_pk_fma_f32 v[104:105], v[88:89], v[104:105], v[118:119]
	v_cvt_pk_bf16_f32 v89, v106, v107
	v_cvt_pk_bf16_f32 v88, v104, v105
	s_waitcnt vmcnt(1)
	v_pk_add_f32 v[90:91], v[94:95], 1.0 op_sel_hi:[1,0]
	v_pk_add_f32 v[92:93], v[92:93], 1.0 op_sel_hi:[1,0]
	s_waitcnt vmcnt(0)
	v_pk_mul_f32 v[90:91], v[98:99], v[90:91]
	v_pk_mul_f32 v[92:93], v[96:97], v[92:93]
	v_pk_mul_f32 v[90:91], v[102:103], v[90:91]
	v_pk_mul_f32 v[92:93], v[100:101], v[92:93]
	v_pk_fma_f32 v[96:97], v[86:87], v[110:111], v[184:185]
	v_cvt_pk_bf16_f32 v92, v92, v93
	v_cvt_pk_bf16_f32 v93, v90, v91
	v_mov_b32_e32 v232, v92
	v_mov_b32_e32 v233, v93
	v_mov_b32_e32 v226, v88
	v_mov_b32_e32 v227, v89
	s_nop 1
	v_permlane16_swap_b32_e32 v224, v226
	v_permlane16_swap_b32_e32 v225, v227
	v_lshl_add_u64 v[244:245], v[122:123], 0, v[248:249]
	global_store_dwordx4 v[244:245], v[224:227], off
	global_load_dwordx4 v[88:91], v[172:173], off offset:64
	s_nop 0
	global_load_dwordx4 v[92:95], v[124:125], off offset:64
	v_pk_fma_f32 v[98:99], v[84:85], v[108:109], v[182:183]
	v_cvt_pk_bf16_f32 v85, v96, v97
	v_cvt_pk_bf16_f32 v84, v98, v99
	s_waitcnt vmcnt(1)
	v_pk_add_f32 v[86:87], v[90:91], 1.0 op_sel_hi:[1,0]
	v_pk_add_f32 v[88:89], v[88:89], 1.0 op_sel_hi:[1,0]
	s_waitcnt vmcnt(0)
	v_pk_mul_f32 v[86:87], v[94:95], v[86:87]
	v_pk_mul_f32 v[88:89], v[92:93], v[88:89]
	v_pk_mul_f32 v[86:87], v[106:107], v[86:87]
	v_pk_mul_f32 v[88:89], v[104:105], v[88:89]
	v_pk_fma_f32 v[92:93], v[82:83], v[116:117], v[188:189]
	v_cvt_pk_bf16_f32 v88, v88, v89
	v_cvt_pk_bf16_f32 v89, v86, v87
	v_mov_b32_e32 v234, v88
	v_mov_b32_e32 v235, v89
	s_nop 1
	v_permlane16_swap_b32_e32 v232, v234
	v_permlane16_swap_b32_e32 v233, v235
	v_lshl_add_u64 v[246:247], v[126:127], 0, v[248:249]
	global_store_dwordx4 v[246:247], v[232:235], off
	v_mov_b32_e32 v236, v84
	v_mov_b32_e32 v237, v85
	global_load_dwordx4 v[84:87], v[172:173], off offset:512
	s_nop 0
	global_load_dwordx4 v[88:91], v[124:125], off offset:512
	v_pk_fma_f32 v[94:95], v[80:81], v[114:115], v[186:187]
	v_cvt_pk_bf16_f32 v81, v92, v93
	v_cvt_pk_bf16_f32 v80, v94, v95
	s_waitcnt vmcnt(1)
	v_pk_add_f32 v[82:83], v[86:87], 1.0 op_sel_hi:[1,0]
	v_pk_add_f32 v[84:85], v[84:85], 1.0 op_sel_hi:[1,0]
	s_waitcnt vmcnt(0)
	v_pk_mul_f32 v[82:83], v[90:91], v[82:83]
	v_pk_mul_f32 v[84:85], v[88:89], v[84:85]
	v_pk_mul_f32 v[82:83], v[96:97], v[82:83]
	v_pk_mul_f32 v[84:85], v[98:99], v[84:85]
	v_mul_f32_e32 v90, v105, v105
	v_cvt_pk_bf16_f32 v84, v84, v85
	v_cvt_pk_bf16_f32 v85, v82, v83
	v_mov_b32_e32 v240, v84
	v_mov_b32_e32 v241, v85
	v_mov_b32_e32 v238, v80
	v_mov_b32_e32 v239, v81
	s_nop 1
	v_permlane16_swap_b32_e32 v236, v238
	v_permlane16_swap_b32_e32 v237, v239
	v_lshl_add_u64 v[244:245], v[122:123], 0, v[248:249]
	global_store_dwordx4 v[244:245], v[236:239], off offset:256
	global_load_dwordx4 v[82:85], v[172:173], off offset:576
	s_nop 0
	global_load_dwordx4 v[86:89], v[124:125], off offset:576
	v_mul_f32_e32 v80, v101, v101
	v_mul_f32_e32 v81, v103, v103
	v_mul_f32_e32 v91, v107, v107
	v_mul_f32_e32 v99, v99, v99
	v_mul_f32_e32 v97, v97, v97
	v_fmac_f32_e32 v80, v100, v100
	v_fmac_f32_e32 v81, v102, v102
	v_fmac_f32_e32 v90, v104, v104
	v_fmac_f32_e32 v91, v106, v106
	v_mul_f32_e32 v101, v95, v95
	v_mul_f32_e32 v103, v93, v93
	v_fmac_f32_e32 v99, v98, v98
	v_fmac_f32_e32 v97, v96, v96
	v_add_f32_e32 v80, v80, v81
	v_add_f32_e32 v81, v90, v91
	v_fmac_f32_e32 v101, v94, v94
	v_fmac_f32_e32 v103, v92, v92
	v_add_f32_e32 v90, v99, v97
	v_add_f32_e32 v80, v80, v81
	v_add_f32_e32 v91, v101, v103
	v_add_f32_e32 v80, v80, v90
	v_add_f32_e32 v80, v80, v91
	ds_bpermute_b32 v81, v112, v80
	s_waitcnt lgkmcnt(0)
	v_add_f32_e32 v80, v80, v81
	ds_bpermute_b32 v81, v113, v80
	s_waitcnt vmcnt(1)
	v_pk_add_f32 v[84:85], v[84:85], 1.0 op_sel_hi:[1,0]
	v_pk_add_f32 v[82:83], v[82:83], 1.0 op_sel_hi:[1,0]
	s_waitcnt vmcnt(0)
	v_pk_mul_f32 v[84:85], v[88:89], v[84:85]
	v_pk_mul_f32 v[82:83], v[86:87], v[82:83]
	v_pk_mul_f32 v[84:85], v[92:93], v[84:85]
	v_pk_mul_f32 v[82:83], v[94:95], v[82:83]
	s_nop 0
	v_cvt_pk_bf16_f32 v82, v82, v83
	v_cvt_pk_bf16_f32 v83, v84, v85
	v_mov_b32_e32 v242, v82
	v_mov_b32_e32 v243, v83
	s_nop 1
	v_permlane16_swap_b32_e32 v240, v242
	v_permlane16_swap_b32_e32 v241, v243
	v_lshl_add_u64 v[246:247], v[126:127], 0, v[248:249]
	global_store_dwordx4 v[246:247], v[240:243], off offset:256
	s_and_saveexec_b64 s[76:77], s[0:1]
	s_cbranch_execz .LBB0_754
	s_waitcnt lgkmcnt(0)
	v_add_f32_e32 v82, v80, v81
	v_lshl_add_u64 v[80:81], v[152:153], 0, s[74:75]
	global_atomic_add_f32 v[80:81], v82, off
.LBB0_754:
	s_or_b64 exec, exec, s[76:77]
	v_lshl_add_u64 v[100:101], v[138:139], 0, v[174:175]
	v_lshl_add_u64 v[108:109], v[100:101], 2, s[86:87]
	s_waitcnt lgkmcnt(0)
	global_load_dwordx4 v[80:83], v[108:109], off
	global_load_dwordx4 v[84:87], v[176:177], off
	global_load_dwordx4 v[88:91], v[176:177], off offset:64
	global_load_dwordx4 v[92:95], v[176:177], off offset:512
	global_load_dwordx4 v[96:99], v[176:177], off offset:576
	v_lshlrev_b64 v[114:115], 1, v[100:101]
	v_lshl_add_u64 v[116:117], s[90:91], 0, v[114:115]
	global_load_dwordx4 v[100:103], v[108:109], off offset:64
	global_load_dwordx4 v[104:107], v[108:109], off offset:512
	s_nop 0
	global_load_dwordx4 v[108:111], v[108:109], off offset:576
	v_lshl_add_u64 v[114:115], s[88:89], 0, v[114:115]
	s_waitcnt vmcnt(6)
	v_pk_fma_f32 v[86:87], v[78:79], v[86:87], v[82:83]
	v_pk_fma_f32 v[84:85], v[76:77], v[84:85], v[80:81]
	v_cvt_pk_bf16_f32 v77, v86, v87
	v_cvt_pk_bf16_f32 v76, v84, v85
	v_mov_b32_e32 v224, v76
	v_mov_b32_e32 v225, v77
	global_load_dwordx4 v[76:79], v[172:173], off
	s_nop 0
	global_load_dwordx4 v[80:83], v[124:125], off
	s_waitcnt vmcnt(4)
	v_pk_fma_f32 v[90:91], v[74:75], v[90:91], v[102:103]
	v_pk_fma_f32 v[88:89], v[72:73], v[88:89], v[100:101]
	v_cvt_pk_bf16_f32 v73, v90, v91
	v_cvt_pk_bf16_f32 v72, v88, v89
	s_waitcnt vmcnt(1)
	v_pk_add_f32 v[74:75], v[78:79], 1.0 op_sel_hi:[1,0]
	v_pk_add_f32 v[76:77], v[76:77], 1.0 op_sel_hi:[1,0]
	s_waitcnt vmcnt(0)
	v_pk_mul_f32 v[74:75], v[82:83], v[74:75]
	v_pk_mul_f32 v[76:77], v[80:81], v[76:77]
	v_pk_mul_f32 v[74:75], v[86:87], v[74:75]
	v_pk_mul_f32 v[76:77], v[84:85], v[76:77]
	v_pk_fma_f32 v[80:81], v[70:71], v[94:95], v[106:107]
	v_cvt_pk_bf16_f32 v76, v76, v77
	v_cvt_pk_bf16_f32 v77, v74, v75
	v_mov_b32_e32 v232, v76
	v_mov_b32_e32 v233, v77
	v_mov_b32_e32 v226, v72
	v_mov_b32_e32 v227, v73
	s_nop 1
	v_permlane16_swap_b32_e32 v224, v226
	v_permlane16_swap_b32_e32 v225, v227
	v_lshl_add_u64 v[244:245], v[116:117], 0, v[248:249]
	global_store_dwordx4 v[244:245], v[224:227], off
	global_load_dwordx4 v[72:75], v[172:173], off offset:64
	s_nop 0
	global_load_dwordx4 v[76:79], v[124:125], off offset:64
	v_pk_fma_f32 v[82:83], v[68:69], v[92:93], v[104:105]
	v_cvt_pk_bf16_f32 v69, v80, v81
	v_cvt_pk_bf16_f32 v68, v82, v83
	s_waitcnt vmcnt(1)
	v_pk_add_f32 v[70:71], v[74:75], 1.0 op_sel_hi:[1,0]
	v_pk_add_f32 v[72:73], v[72:73], 1.0 op_sel_hi:[1,0]
	s_waitcnt vmcnt(0)
	v_pk_mul_f32 v[70:71], v[78:79], v[70:71]
	v_pk_mul_f32 v[72:73], v[76:77], v[72:73]
	v_pk_mul_f32 v[70:71], v[90:91], v[70:71]
	v_pk_mul_f32 v[72:73], v[88:89], v[72:73]
	v_pk_fma_f32 v[76:77], v[66:67], v[98:99], v[110:111]
	v_cvt_pk_bf16_f32 v72, v72, v73
	v_cvt_pk_bf16_f32 v73, v70, v71
	v_mov_b32_e32 v234, v72
	v_mov_b32_e32 v235, v73
	s_nop 1
	v_permlane16_swap_b32_e32 v232, v234
	v_permlane16_swap_b32_e32 v233, v235
	v_lshl_add_u64 v[246:247], v[114:115], 0, v[248:249]
	global_store_dwordx4 v[246:247], v[232:235], off
	v_mov_b32_e32 v236, v68
	v_mov_b32_e32 v237, v69
	global_load_dwordx4 v[68:71], v[172:173], off offset:512
	s_nop 0
	global_load_dwordx4 v[72:75], v[124:125], off offset:512
	v_pk_fma_f32 v[78:79], v[64:65], v[96:97], v[108:109]
	v_cvt_pk_bf16_f32 v65, v76, v77
	v_cvt_pk_bf16_f32 v64, v78, v79
	s_waitcnt vmcnt(1)
	v_pk_add_f32 v[66:67], v[70:71], 1.0 op_sel_hi:[1,0]
	v_pk_add_f32 v[68:69], v[68:69], 1.0 op_sel_hi:[1,0]
	s_waitcnt vmcnt(0)
	v_pk_mul_f32 v[66:67], v[74:75], v[66:67]
	v_pk_mul_f32 v[68:69], v[72:73], v[68:69]
	v_pk_mul_f32 v[66:67], v[80:81], v[66:67]
	v_pk_mul_f32 v[68:69], v[82:83], v[68:69]
	v_mul_f32_e32 v74, v89, v89
	v_cvt_pk_bf16_f32 v68, v68, v69
	v_cvt_pk_bf16_f32 v69, v66, v67
	v_mov_b32_e32 v240, v68
	v_mov_b32_e32 v241, v69
	v_mov_b32_e32 v238, v64
	v_mov_b32_e32 v239, v65
	s_nop 1
	v_permlane16_swap_b32_e32 v236, v238
	v_permlane16_swap_b32_e32 v237, v239
	v_lshl_add_u64 v[244:245], v[116:117], 0, v[248:249]
	global_store_dwordx4 v[244:245], v[236:239], off offset:256
	global_load_dwordx4 v[66:69], v[172:173], off offset:576
	s_nop 0
	global_load_dwordx4 v[70:73], v[124:125], off offset:576
	v_mul_f32_e32 v64, v85, v85
	v_mul_f32_e32 v65, v87, v87
	v_mul_f32_e32 v75, v91, v91
	v_mul_f32_e32 v83, v83, v83
	v_mul_f32_e32 v81, v81, v81
	v_fmac_f32_e32 v64, v84, v84
	v_fmac_f32_e32 v65, v86, v86
	v_fmac_f32_e32 v74, v88, v88
	v_fmac_f32_e32 v75, v90, v90
	v_mul_f32_e32 v85, v79, v79
	v_mul_f32_e32 v87, v77, v77
	v_fmac_f32_e32 v83, v82, v82
	v_fmac_f32_e32 v81, v80, v80
	v_add_f32_e32 v64, v64, v65
	v_add_f32_e32 v65, v74, v75
	v_fmac_f32_e32 v85, v78, v78
	v_fmac_f32_e32 v87, v76, v76
	v_add_f32_e32 v74, v83, v81
	v_add_f32_e32 v64, v64, v65
	v_add_f32_e32 v75, v85, v87
	v_add_f32_e32 v64, v64, v74
	v_add_f32_e32 v64, v64, v75
	ds_bpermute_b32 v65, v112, v64
	s_waitcnt lgkmcnt(0)
	v_add_f32_e32 v64, v64, v65
	ds_bpermute_b32 v65, v113, v64
	s_waitcnt vmcnt(1)
	v_pk_add_f32 v[68:69], v[68:69], 1.0 op_sel_hi:[1,0]
	v_pk_add_f32 v[66:67], v[66:67], 1.0 op_sel_hi:[1,0]
	s_waitcnt vmcnt(0)
	v_pk_mul_f32 v[68:69], v[72:73], v[68:69]
	v_pk_mul_f32 v[66:67], v[70:71], v[66:67]
	v_pk_mul_f32 v[68:69], v[76:77], v[68:69]
	v_pk_mul_f32 v[66:67], v[78:79], v[66:67]
	s_nop 0
	v_cvt_pk_bf16_f32 v66, v66, v67
	v_cvt_pk_bf16_f32 v67, v68, v69
	v_mov_b32_e32 v242, v66
	v_mov_b32_e32 v243, v67
	s_nop 1
	v_permlane16_swap_b32_e32 v240, v242
	v_permlane16_swap_b32_e32 v241, v243
	v_lshl_add_u64 v[246:247], v[114:115], 0, v[248:249]
	global_store_dwordx4 v[246:247], v[240:243], off offset:256
	s_and_saveexec_b64 s[76:77], s[0:1]
	s_cbranch_execz .LBB0_756
	s_waitcnt lgkmcnt(0)
	v_add_f32_e32 v66, v64, v65
	v_lshl_add_u64 v[64:65], v[154:155], 0, s[74:75]
	global_atomic_add_f32 v[64:65], v66, off
.LBB0_756:
	s_or_b64 exec, exec, s[76:77]
	v_lshl_add_u64 v[84:85], v[140:141], 0, v[174:175]
	v_lshl_add_u64 v[92:93], v[84:85], 2, s[86:87]
	s_waitcnt lgkmcnt(0)
	global_load_dwordx4 v[64:67], v[92:93], off
	global_load_dwordx4 v[68:71], v[176:177], off
	global_load_dwordx4 v[72:75], v[176:177], off offset:64
	global_load_dwordx4 v[76:79], v[176:177], off offset:512
	global_load_dwordx4 v[80:83], v[176:177], off offset:576
	v_lshlrev_b64 v[96:97], 1, v[84:85]
	v_lshl_add_u64 v[98:99], s[90:91], 0, v[96:97]
	global_load_dwordx4 v[84:87], v[92:93], off offset:64
	global_load_dwordx4 v[88:91], v[92:93], off offset:512
	s_nop 0
	global_load_dwordx4 v[92:95], v[92:93], off offset:576
	v_lshl_add_u64 v[96:97], s[88:89], 0, v[96:97]
	s_waitcnt vmcnt(6)
	v_pk_fma_f32 v[70:71], v[62:63], v[70:71], v[66:67]
	v_pk_fma_f32 v[68:69], v[60:61], v[68:69], v[64:65]
	v_cvt_pk_bf16_f32 v61, v70, v71
	v_cvt_pk_bf16_f32 v60, v68, v69
	v_mov_b32_e32 v224, v60
	v_mov_b32_e32 v225, v61
	global_load_dwordx4 v[60:63], v[172:173], off
	s_nop 0
	global_load_dwordx4 v[64:67], v[124:125], off
	s_waitcnt vmcnt(4)
	v_pk_fma_f32 v[74:75], v[58:59], v[74:75], v[86:87]
	v_pk_fma_f32 v[72:73], v[56:57], v[72:73], v[84:85]
	v_cvt_pk_bf16_f32 v57, v74, v75
	v_cvt_pk_bf16_f32 v56, v72, v73
	s_waitcnt vmcnt(1)
	v_pk_add_f32 v[58:59], v[62:63], 1.0 op_sel_hi:[1,0]
	v_pk_add_f32 v[60:61], v[60:61], 1.0 op_sel_hi:[1,0]
	s_waitcnt vmcnt(0)
	v_pk_mul_f32 v[58:59], v[66:67], v[58:59]
	v_pk_mul_f32 v[60:61], v[64:65], v[60:61]
	v_pk_mul_f32 v[58:59], v[70:71], v[58:59]
	v_pk_mul_f32 v[60:61], v[68:69], v[60:61]
	v_pk_fma_f32 v[64:65], v[54:55], v[78:79], v[90:91]
	v_cvt_pk_bf16_f32 v60, v60, v61
	v_cvt_pk_bf16_f32 v61, v58, v59
	v_mov_b32_e32 v232, v60
	v_mov_b32_e32 v233, v61
	v_mov_b32_e32 v226, v56
	v_mov_b32_e32 v227, v57
	s_nop 1
	v_permlane16_swap_b32_e32 v224, v226
	v_permlane16_swap_b32_e32 v225, v227
	v_lshl_add_u64 v[244:245], v[98:99], 0, v[248:249]
	global_store_dwordx4 v[244:245], v[224:227], off
	global_load_dwordx4 v[56:59], v[172:173], off offset:64
	s_nop 0
	global_load_dwordx4 v[60:63], v[124:125], off offset:64
	v_pk_fma_f32 v[66:67], v[52:53], v[76:77], v[88:89]
	v_cvt_pk_bf16_f32 v53, v64, v65
	v_cvt_pk_bf16_f32 v52, v66, v67
	s_waitcnt vmcnt(1)
	v_pk_add_f32 v[54:55], v[58:59], 1.0 op_sel_hi:[1,0]
	v_pk_add_f32 v[56:57], v[56:57], 1.0 op_sel_hi:[1,0]
	s_waitcnt vmcnt(0)
	v_pk_mul_f32 v[54:55], v[62:63], v[54:55]
	v_pk_mul_f32 v[56:57], v[60:61], v[56:57]
	v_pk_mul_f32 v[54:55], v[74:75], v[54:55]
	v_pk_mul_f32 v[56:57], v[72:73], v[56:57]
	v_pk_fma_f32 v[60:61], v[50:51], v[82:83], v[94:95]
	v_cvt_pk_bf16_f32 v56, v56, v57
	v_cvt_pk_bf16_f32 v57, v54, v55
	v_mov_b32_e32 v234, v56
	v_mov_b32_e32 v235, v57
	s_nop 1
	v_permlane16_swap_b32_e32 v232, v234
	v_permlane16_swap_b32_e32 v233, v235
	v_lshl_add_u64 v[246:247], v[96:97], 0, v[248:249]
	global_store_dwordx4 v[246:247], v[232:235], off
	v_mov_b32_e32 v236, v52
	v_mov_b32_e32 v237, v53
	global_load_dwordx4 v[52:55], v[172:173], off offset:512
	s_nop 0
	global_load_dwordx4 v[56:59], v[124:125], off offset:512
	v_pk_fma_f32 v[62:63], v[48:49], v[80:81], v[92:93]
	v_cvt_pk_bf16_f32 v49, v60, v61
	v_cvt_pk_bf16_f32 v48, v62, v63
	s_waitcnt vmcnt(1)
	v_pk_add_f32 v[50:51], v[54:55], 1.0 op_sel_hi:[1,0]
	v_pk_add_f32 v[52:53], v[52:53], 1.0 op_sel_hi:[1,0]
	s_waitcnt vmcnt(0)
	v_pk_mul_f32 v[50:51], v[58:59], v[50:51]
	v_pk_mul_f32 v[52:53], v[56:57], v[52:53]
	v_pk_mul_f32 v[50:51], v[64:65], v[50:51]
	v_pk_mul_f32 v[52:53], v[66:67], v[52:53]
	v_mul_f32_e32 v58, v73, v73
	v_cvt_pk_bf16_f32 v52, v52, v53
	v_cvt_pk_bf16_f32 v53, v50, v51
	v_mov_b32_e32 v240, v52
	v_mov_b32_e32 v241, v53
	v_mov_b32_e32 v238, v48
	v_mov_b32_e32 v239, v49
	s_nop 1
	v_permlane16_swap_b32_e32 v236, v238
	v_permlane16_swap_b32_e32 v237, v239
	v_lshl_add_u64 v[244:245], v[98:99], 0, v[248:249]
	global_store_dwordx4 v[244:245], v[236:239], off offset:256
	global_load_dwordx4 v[50:53], v[172:173], off offset:576
	s_nop 0
	global_load_dwordx4 v[54:57], v[124:125], off offset:576
	v_mul_f32_e32 v48, v69, v69
	v_mul_f32_e32 v49, v71, v71
	v_mul_f32_e32 v59, v75, v75
	v_mul_f32_e32 v67, v67, v67
	v_mul_f32_e32 v65, v65, v65
	v_fmac_f32_e32 v48, v68, v68
	v_fmac_f32_e32 v49, v70, v70
	v_fmac_f32_e32 v58, v72, v72
	v_fmac_f32_e32 v59, v74, v74
	v_mul_f32_e32 v69, v63, v63
	v_mul_f32_e32 v71, v61, v61
	v_fmac_f32_e32 v67, v66, v66
	v_fmac_f32_e32 v65, v64, v64
	v_add_f32_e32 v48, v48, v49
	v_add_f32_e32 v49, v58, v59
	v_fmac_f32_e32 v69, v62, v62
	v_fmac_f32_e32 v71, v60, v60
	v_add_f32_e32 v58, v67, v65
	v_add_f32_e32 v48, v48, v49
	v_add_f32_e32 v59, v69, v71
	v_add_f32_e32 v48, v48, v58
	v_add_f32_e32 v48, v48, v59
	ds_bpermute_b32 v49, v112, v48
	s_waitcnt lgkmcnt(0)
	v_add_f32_e32 v48, v48, v49
	ds_bpermute_b32 v49, v113, v48
	s_waitcnt vmcnt(1)
	v_pk_add_f32 v[52:53], v[52:53], 1.0 op_sel_hi:[1,0]
	v_pk_add_f32 v[50:51], v[50:51], 1.0 op_sel_hi:[1,0]
	s_waitcnt vmcnt(0)
	v_pk_mul_f32 v[52:53], v[56:57], v[52:53]
	v_pk_mul_f32 v[50:51], v[54:55], v[50:51]
	v_pk_mul_f32 v[52:53], v[60:61], v[52:53]
	v_pk_mul_f32 v[50:51], v[62:63], v[50:51]
	s_nop 0
	v_cvt_pk_bf16_f32 v50, v50, v51
	v_cvt_pk_bf16_f32 v51, v52, v53
	v_mov_b32_e32 v242, v50
	v_mov_b32_e32 v243, v51
	s_nop 1
	v_permlane16_swap_b32_e32 v240, v242
	v_permlane16_swap_b32_e32 v241, v243
	v_lshl_add_u64 v[246:247], v[96:97], 0, v[248:249]
	global_store_dwordx4 v[246:247], v[240:243], off offset:256
	s_and_saveexec_b64 s[76:77], s[0:1]
	s_cbranch_execz .LBB0_758
	s_waitcnt lgkmcnt(0)
	v_add_f32_e32 v50, v48, v49
	v_lshl_add_u64 v[48:49], v[156:157], 0, s[74:75]
	global_atomic_add_f32 v[48:49], v50, off
.LBB0_758:
	s_or_b64 exec, exec, s[76:77]
	v_lshl_add_u64 v[68:69], v[142:143], 0, v[174:175]
	v_lshl_add_u64 v[76:77], v[68:69], 2, s[86:87]
	s_waitcnt lgkmcnt(0)
	global_load_dwordx4 v[48:51], v[76:77], off
	global_load_dwordx4 v[52:55], v[176:177], off
	global_load_dwordx4 v[56:59], v[176:177], off offset:64
	global_load_dwordx4 v[60:63], v[176:177], off offset:512
	global_load_dwordx4 v[64:67], v[176:177], off offset:576
	v_lshlrev_b64 v[80:81], 1, v[68:69]
	v_lshl_add_u64 v[82:83], s[90:91], 0, v[80:81]
	global_load_dwordx4 v[68:71], v[76:77], off offset:64
	global_load_dwordx4 v[72:75], v[76:77], off offset:512
	s_nop 0
	global_load_dwordx4 v[76:79], v[76:77], off offset:576
	v_lshl_add_u64 v[80:81], s[88:89], 0, v[80:81]
	s_waitcnt vmcnt(6)
	v_pk_fma_f32 v[54:55], v[46:47], v[54:55], v[50:51]
	v_pk_fma_f32 v[52:53], v[44:45], v[52:53], v[48:49]
	v_cvt_pk_bf16_f32 v45, v54, v55
	v_cvt_pk_bf16_f32 v44, v52, v53
	v_mov_b32_e32 v224, v44
	v_mov_b32_e32 v225, v45
	global_load_dwordx4 v[44:47], v[172:173], off
	s_nop 0
	global_load_dwordx4 v[48:51], v[124:125], off
	s_waitcnt vmcnt(4)
	v_pk_fma_f32 v[58:59], v[42:43], v[58:59], v[70:71]
	v_pk_fma_f32 v[56:57], v[40:41], v[56:57], v[68:69]
	v_cvt_pk_bf16_f32 v41, v58, v59
	v_cvt_pk_bf16_f32 v40, v56, v57
	s_waitcnt vmcnt(1)
	v_pk_add_f32 v[42:43], v[46:47], 1.0 op_sel_hi:[1,0]
	v_pk_add_f32 v[44:45], v[44:45], 1.0 op_sel_hi:[1,0]
	s_waitcnt vmcnt(0)
	v_pk_mul_f32 v[42:43], v[50:51], v[42:43]
	v_pk_mul_f32 v[44:45], v[48:49], v[44:45]
	v_pk_mul_f32 v[42:43], v[54:55], v[42:43]
	v_pk_mul_f32 v[44:45], v[52:53], v[44:45]
	v_pk_fma_f32 v[48:49], v[38:39], v[62:63], v[74:75]
	v_cvt_pk_bf16_f32 v44, v44, v45
	v_cvt_pk_bf16_f32 v45, v42, v43
	v_mov_b32_e32 v232, v44
	v_mov_b32_e32 v233, v45
	v_mov_b32_e32 v226, v40
	v_mov_b32_e32 v227, v41
	s_nop 1
	v_permlane16_swap_b32_e32 v224, v226
	v_permlane16_swap_b32_e32 v225, v227
	v_lshl_add_u64 v[244:245], v[82:83], 0, v[248:249]
	global_store_dwordx4 v[244:245], v[224:227], off
	global_load_dwordx4 v[40:43], v[172:173], off offset:64
	s_nop 0
	global_load_dwordx4 v[44:47], v[124:125], off offset:64
	v_pk_fma_f32 v[50:51], v[36:37], v[60:61], v[72:73]
	v_cvt_pk_bf16_f32 v37, v48, v49
	v_cvt_pk_bf16_f32 v36, v50, v51
	s_waitcnt vmcnt(1)
	v_pk_add_f32 v[38:39], v[42:43], 1.0 op_sel_hi:[1,0]
	v_pk_add_f32 v[40:41], v[40:41], 1.0 op_sel_hi:[1,0]
	s_waitcnt vmcnt(0)
	v_pk_mul_f32 v[38:39], v[46:47], v[38:39]
	v_pk_mul_f32 v[40:41], v[44:45], v[40:41]
	v_pk_mul_f32 v[38:39], v[58:59], v[38:39]
	v_pk_mul_f32 v[40:41], v[56:57], v[40:41]
	v_pk_fma_f32 v[44:45], v[34:35], v[66:67], v[78:79]
	v_cvt_pk_bf16_f32 v40, v40, v41
	v_cvt_pk_bf16_f32 v41, v38, v39
	v_mov_b32_e32 v234, v40
	v_mov_b32_e32 v235, v41
	s_nop 1
	v_permlane16_swap_b32_e32 v232, v234
	v_permlane16_swap_b32_e32 v233, v235
	v_lshl_add_u64 v[246:247], v[80:81], 0, v[248:249]
	global_store_dwordx4 v[246:247], v[232:235], off
	v_mov_b32_e32 v236, v36
	v_mov_b32_e32 v237, v37
	global_load_dwordx4 v[36:39], v[172:173], off offset:512
	s_nop 0
	global_load_dwordx4 v[40:43], v[124:125], off offset:512
	v_pk_fma_f32 v[46:47], v[32:33], v[64:65], v[76:77]
	v_cvt_pk_bf16_f32 v33, v44, v45
	v_cvt_pk_bf16_f32 v32, v46, v47
	s_waitcnt vmcnt(1)
	v_pk_add_f32 v[34:35], v[38:39], 1.0 op_sel_hi:[1,0]
	v_pk_add_f32 v[36:37], v[36:37], 1.0 op_sel_hi:[1,0]
	s_waitcnt vmcnt(0)
	v_pk_mul_f32 v[34:35], v[42:43], v[34:35]
	v_pk_mul_f32 v[36:37], v[40:41], v[36:37]
	v_pk_mul_f32 v[34:35], v[48:49], v[34:35]
	v_pk_mul_f32 v[36:37], v[50:51], v[36:37]
	v_mul_f32_e32 v42, v57, v57
	v_cvt_pk_bf16_f32 v36, v36, v37
	v_cvt_pk_bf16_f32 v37, v34, v35
	v_mov_b32_e32 v240, v36
	v_mov_b32_e32 v241, v37
	v_mov_b32_e32 v238, v32
	v_mov_b32_e32 v239, v33
	s_nop 1
	v_permlane16_swap_b32_e32 v236, v238
	v_permlane16_swap_b32_e32 v237, v239
	v_lshl_add_u64 v[244:245], v[82:83], 0, v[248:249]
	global_store_dwordx4 v[244:245], v[236:239], off offset:256
	global_load_dwordx4 v[34:37], v[172:173], off offset:576
	s_nop 0
	global_load_dwordx4 v[38:41], v[124:125], off offset:576
	v_mul_f32_e32 v32, v53, v53
	v_mul_f32_e32 v33, v55, v55
	v_mul_f32_e32 v43, v59, v59
	v_mul_f32_e32 v51, v51, v51
	v_mul_f32_e32 v49, v49, v49
	v_fmac_f32_e32 v32, v52, v52
	v_fmac_f32_e32 v33, v54, v54
	v_fmac_f32_e32 v42, v56, v56
	v_fmac_f32_e32 v43, v58, v58
	v_mul_f32_e32 v53, v47, v47
	v_mul_f32_e32 v55, v45, v45
	v_fmac_f32_e32 v51, v50, v50
	v_fmac_f32_e32 v49, v48, v48
	v_add_f32_e32 v32, v32, v33
	v_add_f32_e32 v33, v42, v43
	v_fmac_f32_e32 v53, v46, v46
	v_fmac_f32_e32 v55, v44, v44
	v_add_f32_e32 v42, v51, v49
	v_add_f32_e32 v32, v32, v33
	v_add_f32_e32 v43, v53, v55
	v_add_f32_e32 v32, v32, v42
	v_add_f32_e32 v32, v32, v43
	ds_bpermute_b32 v33, v112, v32
	s_waitcnt lgkmcnt(0)
	v_add_f32_e32 v32, v32, v33
	ds_bpermute_b32 v33, v113, v32
	s_waitcnt vmcnt(1)
	v_pk_add_f32 v[36:37], v[36:37], 1.0 op_sel_hi:[1,0]
	v_pk_add_f32 v[34:35], v[34:35], 1.0 op_sel_hi:[1,0]
	s_waitcnt vmcnt(0)
	v_pk_mul_f32 v[36:37], v[40:41], v[36:37]
	v_pk_mul_f32 v[34:35], v[38:39], v[34:35]
	v_pk_mul_f32 v[36:37], v[44:45], v[36:37]
	v_pk_mul_f32 v[34:35], v[46:47], v[34:35]
	s_nop 0
	v_cvt_pk_bf16_f32 v34, v34, v35
	v_cvt_pk_bf16_f32 v35, v36, v37
	v_mov_b32_e32 v242, v34
	v_mov_b32_e32 v243, v35
	s_nop 1
	v_permlane16_swap_b32_e32 v240, v242
	v_permlane16_swap_b32_e32 v241, v243
	v_lshl_add_u64 v[246:247], v[80:81], 0, v[248:249]
	global_store_dwordx4 v[246:247], v[240:243], off offset:256
	s_and_saveexec_b64 s[76:77], s[0:1]
	s_cbranch_execz .LBB0_760
	s_waitcnt lgkmcnt(0)
	v_add_f32_e32 v34, v32, v33
	v_lshl_add_u64 v[32:33], v[158:159], 0, s[74:75]
	global_atomic_add_f32 v[32:33], v34, off
.LBB0_760:
	s_or_b64 exec, exec, s[76:77]
	v_lshl_add_u64 v[52:53], v[144:145], 0, v[174:175]
	v_lshl_add_u64 v[60:61], v[52:53], 2, s[86:87]
	s_waitcnt lgkmcnt(0)
	global_load_dwordx4 v[32:35], v[60:61], off
	global_load_dwordx4 v[36:39], v[176:177], off
	global_load_dwordx4 v[40:43], v[176:177], off offset:64
	global_load_dwordx4 v[44:47], v[176:177], off offset:512
	global_load_dwordx4 v[48:51], v[176:177], off offset:576
	v_lshlrev_b64 v[64:65], 1, v[52:53]
	v_lshl_add_u64 v[66:67], s[90:91], 0, v[64:65]
	global_load_dwordx4 v[52:55], v[60:61], off offset:64
	global_load_dwordx4 v[56:59], v[60:61], off offset:512
	s_nop 0
	global_load_dwordx4 v[60:63], v[60:61], off offset:576
	v_lshl_add_u64 v[64:65], s[88:89], 0, v[64:65]
	s_waitcnt vmcnt(6)
	v_pk_fma_f32 v[38:39], v[30:31], v[38:39], v[34:35]
	v_pk_fma_f32 v[36:37], v[28:29], v[36:37], v[32:33]
	v_cvt_pk_bf16_f32 v29, v38, v39
	v_cvt_pk_bf16_f32 v28, v36, v37
	v_mov_b32_e32 v224, v28
	v_mov_b32_e32 v225, v29
	global_load_dwordx4 v[28:31], v[172:173], off
	s_nop 0
	global_load_dwordx4 v[32:35], v[124:125], off
	s_waitcnt vmcnt(4)
	v_pk_fma_f32 v[42:43], v[26:27], v[42:43], v[54:55]
	v_pk_fma_f32 v[40:41], v[24:25], v[40:41], v[52:53]
	v_cvt_pk_bf16_f32 v25, v42, v43
	v_cvt_pk_bf16_f32 v24, v40, v41
	s_waitcnt vmcnt(1)
	v_pk_add_f32 v[26:27], v[30:31], 1.0 op_sel_hi:[1,0]
	v_pk_add_f32 v[28:29], v[28:29], 1.0 op_sel_hi:[1,0]
	s_waitcnt vmcnt(0)
	v_pk_mul_f32 v[26:27], v[34:35], v[26:27]
	v_pk_mul_f32 v[28:29], v[32:33], v[28:29]
	v_pk_mul_f32 v[26:27], v[38:39], v[26:27]
	v_pk_mul_f32 v[28:29], v[36:37], v[28:29]
	v_pk_fma_f32 v[32:33], v[22:23], v[46:47], v[58:59]
	v_cvt_pk_bf16_f32 v28, v28, v29
	v_cvt_pk_bf16_f32 v29, v26, v27
	v_mov_b32_e32 v232, v28
	v_mov_b32_e32 v233, v29
	v_mov_b32_e32 v226, v24
	v_mov_b32_e32 v227, v25
	s_nop 1
	v_permlane16_swap_b32_e32 v224, v226
	v_permlane16_swap_b32_e32 v225, v227
	v_lshl_add_u64 v[244:245], v[66:67], 0, v[248:249]
	global_store_dwordx4 v[244:245], v[224:227], off
	global_load_dwordx4 v[24:27], v[172:173], off offset:64
	s_nop 0
	global_load_dwordx4 v[28:31], v[124:125], off offset:64
	v_pk_fma_f32 v[34:35], v[20:21], v[44:45], v[56:57]
	v_cvt_pk_bf16_f32 v21, v32, v33
	v_cvt_pk_bf16_f32 v20, v34, v35
	s_waitcnt vmcnt(1)
	v_pk_add_f32 v[22:23], v[26:27], 1.0 op_sel_hi:[1,0]
	v_pk_add_f32 v[24:25], v[24:25], 1.0 op_sel_hi:[1,0]
	s_waitcnt vmcnt(0)
	v_pk_mul_f32 v[22:23], v[30:31], v[22:23]
	v_pk_mul_f32 v[24:25], v[28:29], v[24:25]
	v_pk_mul_f32 v[22:23], v[42:43], v[22:23]
	v_pk_mul_f32 v[24:25], v[40:41], v[24:25]
	v_pk_fma_f32 v[28:29], v[18:19], v[50:51], v[62:63]
	v_cvt_pk_bf16_f32 v24, v24, v25
	v_cvt_pk_bf16_f32 v25, v22, v23
	v_mov_b32_e32 v234, v24
	v_mov_b32_e32 v235, v25
	s_nop 1
	v_permlane16_swap_b32_e32 v232, v234
	v_permlane16_swap_b32_e32 v233, v235
	v_lshl_add_u64 v[246:247], v[64:65], 0, v[248:249]
	global_store_dwordx4 v[246:247], v[232:235], off
	v_mov_b32_e32 v236, v20
	v_mov_b32_e32 v237, v21
	global_load_dwordx4 v[20:23], v[172:173], off offset:512
	s_nop 0
	global_load_dwordx4 v[24:27], v[124:125], off offset:512
	v_pk_fma_f32 v[30:31], v[16:17], v[48:49], v[60:61]
	v_cvt_pk_bf16_f32 v17, v28, v29
	v_cvt_pk_bf16_f32 v16, v30, v31
	s_waitcnt vmcnt(1)
	v_pk_add_f32 v[18:19], v[22:23], 1.0 op_sel_hi:[1,0]
	v_pk_add_f32 v[20:21], v[20:21], 1.0 op_sel_hi:[1,0]
	s_waitcnt vmcnt(0)
	v_pk_mul_f32 v[18:19], v[26:27], v[18:19]
	v_pk_mul_f32 v[20:21], v[24:25], v[20:21]
	v_pk_mul_f32 v[18:19], v[32:33], v[18:19]
	v_pk_mul_f32 v[20:21], v[34:35], v[20:21]
	v_mul_f32_e32 v26, v41, v41
	v_cvt_pk_bf16_f32 v20, v20, v21
	v_cvt_pk_bf16_f32 v21, v18, v19
	v_mov_b32_e32 v240, v20
	v_mov_b32_e32 v241, v21
	v_mov_b32_e32 v238, v16
	v_mov_b32_e32 v239, v17
	s_nop 1
	v_permlane16_swap_b32_e32 v236, v238
	v_permlane16_swap_b32_e32 v237, v239
	v_lshl_add_u64 v[244:245], v[66:67], 0, v[248:249]
	global_store_dwordx4 v[244:245], v[236:239], off offset:256
	global_load_dwordx4 v[18:21], v[172:173], off offset:576
	s_nop 0
	global_load_dwordx4 v[22:25], v[124:125], off offset:576
	v_mul_f32_e32 v16, v37, v37
	v_mul_f32_e32 v17, v39, v39
	v_mul_f32_e32 v27, v43, v43
	v_mul_f32_e32 v35, v35, v35
	v_mul_f32_e32 v33, v33, v33
	v_fmac_f32_e32 v16, v36, v36
	v_fmac_f32_e32 v17, v38, v38
	v_fmac_f32_e32 v26, v40, v40
	v_fmac_f32_e32 v27, v42, v42
	v_mul_f32_e32 v37, v31, v31
	v_mul_f32_e32 v39, v29, v29
	v_fmac_f32_e32 v35, v34, v34
	v_fmac_f32_e32 v33, v32, v32
	v_add_f32_e32 v16, v16, v17
	v_add_f32_e32 v17, v26, v27
	v_fmac_f32_e32 v37, v30, v30
	v_fmac_f32_e32 v39, v28, v28
	v_add_f32_e32 v26, v35, v33
	v_add_f32_e32 v16, v16, v17
	v_add_f32_e32 v27, v37, v39
	v_add_f32_e32 v16, v16, v26
	v_add_f32_e32 v16, v16, v27
	ds_bpermute_b32 v17, v112, v16
	s_waitcnt lgkmcnt(0)
	v_add_f32_e32 v16, v16, v17
	ds_bpermute_b32 v17, v113, v16
	s_waitcnt vmcnt(1)
	v_pk_add_f32 v[20:21], v[20:21], 1.0 op_sel_hi:[1,0]
	v_pk_add_f32 v[18:19], v[18:19], 1.0 op_sel_hi:[1,0]
	s_waitcnt vmcnt(0)
	v_pk_mul_f32 v[20:21], v[24:25], v[20:21]
	v_pk_mul_f32 v[18:19], v[22:23], v[18:19]
	v_pk_mul_f32 v[20:21], v[28:29], v[20:21]
	v_pk_mul_f32 v[18:19], v[30:31], v[18:19]
	s_nop 0
	v_cvt_pk_bf16_f32 v18, v18, v19
	v_cvt_pk_bf16_f32 v19, v20, v21
	v_mov_b32_e32 v242, v18
	v_mov_b32_e32 v243, v19
	s_nop 1
	v_permlane16_swap_b32_e32 v240, v242
	v_permlane16_swap_b32_e32 v241, v243
	v_lshl_add_u64 v[246:247], v[64:65], 0, v[248:249]
	global_store_dwordx4 v[246:247], v[240:243], off offset:256
	s_and_saveexec_b64 s[76:77], s[0:1]
	s_cbranch_execz .LBB0_762
	s_waitcnt lgkmcnt(0)
	v_add_f32_e32 v18, v16, v17
	v_lshl_add_u64 v[16:17], v[160:161], 0, s[74:75]
	global_atomic_add_f32 v[16:17], v18, off
.LBB0_762:
	s_or_b64 exec, exec, s[76:77]
	v_lshl_add_u64 v[36:37], v[146:147], 0, v[174:175]
	v_lshl_add_u64 v[44:45], v[36:37], 2, s[86:87]
	s_waitcnt lgkmcnt(0)
	global_load_dwordx4 v[16:19], v[44:45], off
	global_load_dwordx4 v[20:23], v[176:177], off
	global_load_dwordx4 v[24:27], v[176:177], off offset:64
	global_load_dwordx4 v[28:31], v[176:177], off offset:512
	global_load_dwordx4 v[32:35], v[176:177], off offset:576
	v_lshlrev_b64 v[48:49], 1, v[36:37]
	v_lshl_add_u64 v[50:51], s[90:91], 0, v[48:49]
	global_load_dwordx4 v[36:39], v[44:45], off offset:64
	global_load_dwordx4 v[40:43], v[44:45], off offset:512
	s_nop 0
	global_load_dwordx4 v[44:47], v[44:45], off offset:576
	v_lshl_add_u64 v[48:49], s[88:89], 0, v[48:49]
	s_waitcnt vmcnt(6)
	v_pk_fma_f32 v[22:23], v[14:15], v[22:23], v[18:19]
	v_pk_fma_f32 v[20:21], v[12:13], v[20:21], v[16:17]
	v_cvt_pk_bf16_f32 v13, v22, v23
	v_cvt_pk_bf16_f32 v12, v20, v21
	v_mov_b32_e32 v224, v12
	v_mov_b32_e32 v225, v13
	global_load_dwordx4 v[12:15], v[172:173], off
	s_nop 0
	global_load_dwordx4 v[16:19], v[124:125], off
	s_waitcnt vmcnt(4)
	v_pk_fma_f32 v[26:27], v[10:11], v[26:27], v[38:39]
	v_pk_fma_f32 v[24:25], v[8:9], v[24:25], v[36:37]
	v_cvt_pk_bf16_f32 v9, v26, v27
	v_cvt_pk_bf16_f32 v8, v24, v25
	s_waitcnt vmcnt(1)
	v_pk_add_f32 v[10:11], v[14:15], 1.0 op_sel_hi:[1,0]
	v_pk_add_f32 v[12:13], v[12:13], 1.0 op_sel_hi:[1,0]
	s_waitcnt vmcnt(0)
	v_pk_mul_f32 v[10:11], v[18:19], v[10:11]
	v_pk_mul_f32 v[12:13], v[16:17], v[12:13]
	v_pk_mul_f32 v[10:11], v[22:23], v[10:11]
	v_pk_mul_f32 v[12:13], v[20:21], v[12:13]
	v_pk_fma_f32 v[16:17], v[6:7], v[30:31], v[42:43]
	v_cvt_pk_bf16_f32 v12, v12, v13
	v_cvt_pk_bf16_f32 v13, v10, v11
	v_mov_b32_e32 v232, v12
	v_mov_b32_e32 v233, v13
	v_mov_b32_e32 v226, v8
	v_mov_b32_e32 v227, v9
	s_nop 1
	v_permlane16_swap_b32_e32 v224, v226
	v_permlane16_swap_b32_e32 v225, v227
	v_lshl_add_u64 v[244:245], v[50:51], 0, v[248:249]
	global_store_dwordx4 v[244:245], v[224:227], off
	global_load_dwordx4 v[8:11], v[172:173], off offset:64
	s_nop 0
	global_load_dwordx4 v[12:15], v[124:125], off offset:64
	v_pk_fma_f32 v[18:19], v[4:5], v[28:29], v[40:41]
	v_cvt_pk_bf16_f32 v5, v16, v17
	v_cvt_pk_bf16_f32 v4, v18, v19
	s_waitcnt vmcnt(1)
	v_pk_add_f32 v[6:7], v[10:11], 1.0 op_sel_hi:[1,0]
	v_pk_add_f32 v[8:9], v[8:9], 1.0 op_sel_hi:[1,0]
	s_waitcnt vmcnt(0)
	v_pk_mul_f32 v[6:7], v[14:15], v[6:7]
	v_pk_mul_f32 v[8:9], v[12:13], v[8:9]
	v_pk_mul_f32 v[6:7], v[26:27], v[6:7]
	v_pk_mul_f32 v[8:9], v[24:25], v[8:9]
	v_pk_fma_f32 v[12:13], v[2:3], v[34:35], v[46:47]
	v_cvt_pk_bf16_f32 v8, v8, v9
	v_cvt_pk_bf16_f32 v9, v6, v7
	v_mov_b32_e32 v234, v8
	v_mov_b32_e32 v235, v9
	s_nop 1
	v_permlane16_swap_b32_e32 v232, v234
	v_permlane16_swap_b32_e32 v233, v235
	v_lshl_add_u64 v[246:247], v[48:49], 0, v[248:249]
	global_store_dwordx4 v[246:247], v[232:235], off
	v_mov_b32_e32 v236, v4
	v_mov_b32_e32 v237, v5
	global_load_dwordx4 v[4:7], v[172:173], off offset:512
	s_nop 0
	global_load_dwordx4 v[8:11], v[124:125], off offset:512
	v_pk_fma_f32 v[14:15], v[0:1], v[32:33], v[44:45]
	v_cvt_pk_bf16_f32 v1, v12, v13
	v_cvt_pk_bf16_f32 v0, v14, v15
	s_waitcnt vmcnt(1)
	v_pk_add_f32 v[2:3], v[6:7], 1.0 op_sel_hi:[1,0]
	v_pk_add_f32 v[4:5], v[4:5], 1.0 op_sel_hi:[1,0]
	s_waitcnt vmcnt(0)
	v_pk_mul_f32 v[2:3], v[10:11], v[2:3]
	v_pk_mul_f32 v[4:5], v[8:9], v[4:5]
	v_pk_mul_f32 v[2:3], v[16:17], v[2:3]
	v_pk_mul_f32 v[4:5], v[18:19], v[4:5]
	v_mul_f32_e32 v10, v25, v25
	v_cvt_pk_bf16_f32 v4, v4, v5
	v_cvt_pk_bf16_f32 v5, v2, v3
	v_mov_b32_e32 v240, v4
	v_mov_b32_e32 v241, v5
	v_mov_b32_e32 v238, v0
	v_mov_b32_e32 v239, v1
	s_nop 1
	v_permlane16_swap_b32_e32 v236, v238
	v_permlane16_swap_b32_e32 v237, v239
	v_lshl_add_u64 v[244:245], v[50:51], 0, v[248:249]
	global_store_dwordx4 v[244:245], v[236:239], off offset:256
	global_load_dwordx4 v[2:5], v[172:173], off offset:576
	s_nop 0
	global_load_dwordx4 v[6:9], v[124:125], off offset:576
	v_mul_f32_e32 v0, v21, v21
	v_mul_f32_e32 v1, v23, v23
	v_mul_f32_e32 v11, v27, v27
	v_mul_f32_e32 v19, v19, v19
	v_mul_f32_e32 v17, v17, v17
	v_fmac_f32_e32 v0, v20, v20
	v_fmac_f32_e32 v1, v22, v22
	v_fmac_f32_e32 v10, v24, v24
	v_fmac_f32_e32 v11, v26, v26
	v_mul_f32_e32 v21, v15, v15
	v_mul_f32_e32 v23, v13, v13
	v_fmac_f32_e32 v19, v18, v18
	v_fmac_f32_e32 v17, v16, v16
	v_add_f32_e32 v0, v0, v1
	v_add_f32_e32 v1, v10, v11
	v_fmac_f32_e32 v21, v14, v14
	v_fmac_f32_e32 v23, v12, v12
	v_add_f32_e32 v10, v19, v17
	v_add_f32_e32 v0, v0, v1
	v_add_f32_e32 v11, v21, v23
	v_add_f32_e32 v0, v0, v10
	v_add_f32_e32 v0, v0, v11
	ds_bpermute_b32 v1, v112, v0
	s_waitcnt lgkmcnt(0)
	v_add_f32_e32 v0, v0, v1
	ds_bpermute_b32 v1, v113, v0
	s_waitcnt vmcnt(1)
	v_pk_add_f32 v[4:5], v[4:5], 1.0 op_sel_hi:[1,0]
	v_pk_add_f32 v[2:3], v[2:3], 1.0 op_sel_hi:[1,0]
	s_waitcnt vmcnt(0)
	v_pk_mul_f32 v[4:5], v[8:9], v[4:5]
	v_pk_mul_f32 v[2:3], v[6:7], v[2:3]
	v_pk_mul_f32 v[4:5], v[12:13], v[4:5]
	v_pk_mul_f32 v[2:3], v[14:15], v[2:3]
	s_nop 0
	v_cvt_pk_bf16_f32 v2, v2, v3
	v_cvt_pk_bf16_f32 v3, v4, v5
	v_mov_b32_e32 v242, v2
	v_mov_b32_e32 v243, v3
	s_nop 1
	v_permlane16_swap_b32_e32 v240, v242
	v_permlane16_swap_b32_e32 v241, v243
	v_lshl_add_u64 v[246:247], v[48:49], 0, v[248:249]
	global_store_dwordx4 v[246:247], v[240:243], off offset:256
	s_and_saveexec_b64 s[76:77], s[0:1]
	s_cbranch_execz .LBB0_764
	s_waitcnt lgkmcnt(0)
	v_add_f32_e32 v2, v0, v1
	v_lshl_add_u64 v[0:1], v[162:163], 0, s[74:75]
	global_atomic_add_f32 v[0:1], v2, off
